# out-proj epilogue: 4 x-loads per trip in flight, counted vmcnt (on top of rot8)
# speedup vs baseline: 1.0088x; 1.0088x over previous
.LBB0_624:
	v_lshl_add_u64 v[124:125], v[116:117], 0, s[76:77]
	global_load_dwordx4 v[146:149], v[124:125], off nt
	v_add_co_u32_e32 v244, vcc, 0x20000, v124
	s_nop 1
	v_addc_co_u32_e32 v245, vcc, 0, v125, vcc
	global_load_dwordx4 v[244:247], v[244:245], off nt
	v_add_co_u32_e32 v248, vcc, 0x40000, v124
	s_nop 1
	v_addc_co_u32_e32 v249, vcc, 0, v125, vcc
	global_load_dwordx4 v[248:251], v[248:249], off nt
	v_add_co_u32_e32 v252, vcc, 0x60000, v124
	s_nop 1
	v_addc_co_u32_e32 v253, vcc, 0, v125, vcc
	global_load_dwordx4 v[252:255], v[252:253], off nt
	ds_read_b128 v[150:153], v132
	v_lshl_add_u64 v[122:123], v[102:103], 0, s[76:77]
	v_lshl_add_u64 v[120:121], s[72:73], 0, v[100:101]
	v_add_co_u32_e32 v154, vcc, s15, v120
	s_waitcnt vmcnt(3) lgkmcnt(0)
	v_pk_fma_f32 v[148:149], v[98:99], v[152:153], v[148:149]
	v_pk_fma_f32 v[146:147], v[96:97], v[150:151], v[146:147]
	global_store_dwordx4 v[122:123], v[146:149], off
	v_mul_f32_e32 v150, v142, v146
	v_mul_f32_e32 v151, v143, v147
	v_pk_mul_f32 v[146:147], v[146:147], v[146:147]
	v_mul_f32_e32 v152, v144, v148
	v_mul_f32_e32 v153, v145, v149
	v_pk_mul_f32 v[148:149], v[148:149], v[148:149]
	v_add_f32_e32 v146, v146, v147
	v_add_f32_e32 v146, v148, v146
	v_add_f32_e32 v146, v149, v146
	v_addc_co_u32_e32 v155, vcc, 0, v121, vcc
	s_nop 0
	v_add_f32_dpp v146, v146, v146 quad_perm:[1,0,3,2] row_mask:0xf bank_mask:0xf bound_ctrl:1
	v_cvt_pk_bf16_f32 v150, v150, v151
	v_cvt_pk_bf16_f32 v151, v152, v153
	global_store_dwordx2 v[154:155], v[150:151], off
	s_nop 0
	v_add_f32_dpp v146, v146, v146 quad_perm:[2,3,0,1] row_mask:0xf bank_mask:0xf bound_ctrl:1
	s_nop 1
	v_add_f32_dpp v146, v146, v146 row_half_mirror row_mask:0xf bank_mask:0xf bound_ctrl:1
	s_nop 1
	v_add_f32_dpp v146, v146, v146 row_mirror row_mask:0xf bank_mask:0xf bound_ctrl:1
	v_mov_b32_e32 v147, v146
	s_nop 1
	v_permlane16_swap_b32_e32 v146, v147
	s_and_saveexec_b64 s[78:79], s[4:5]
	s_cbranch_execz .LBB0_626
	v_lshl_add_u64 v[148:149], s[72:73], 0, v[118:119]
	v_add_f32_e32 v146, v146, v147
	global_store_dword v[148:149], v146, off offset:-2048
.LBB0_626:
	s_or_b64 exec, exec, s[78:79]
	ds_read_b128 v[150:153], v132 offset:8704
	s_nop 0
	v_add_co_u32_e32 v154, vcc, s22, v122
	s_waitcnt vmcnt(5) lgkmcnt(0)
	v_pk_fma_f32 v[246:247], v[98:99], v[152:153], v[246:247]
	v_addc_co_u32_e32 v155, vcc, 0, v123, vcc
	v_pk_fma_f32 v[244:245], v[96:97], v[150:151], v[244:245]
	global_store_dwordx4 v[154:155], v[244:247], off
	v_mul_f32_e32 v150, v142, v244
	v_mul_f32_e32 v151, v143, v245
	v_pk_mul_f32 v[244:245], v[244:245], v[244:245]
	v_mul_f32_e32 v152, v144, v246
	v_mul_f32_e32 v153, v145, v247
	v_pk_mul_f32 v[246:247], v[246:247], v[246:247]
	v_add_f32_e32 v244, v244, v245
	v_add_f32_e32 v244, v246, v244
	v_add_f32_e32 v244, v247, v244
	v_add_co_u32_e32 v158, vcc, s33, v120
	s_nop 0
	v_add_f32_dpp v244, v244, v244 quad_perm:[1,0,3,2] row_mask:0xf bank_mask:0xf bound_ctrl:1
	v_addc_co_u32_e32 v159, vcc, 0, v121, vcc
	s_nop 0
	v_add_f32_dpp v244, v244, v244 quad_perm:[2,3,0,1] row_mask:0xf bank_mask:0xf bound_ctrl:1
	v_cvt_pk_bf16_f32 v150, v150, v151
	v_cvt_pk_bf16_f32 v151, v152, v153
	global_store_dwordx2 v[158:159], v[150:151], off
	s_nop 0
	v_add_f32_dpp v244, v244, v244 row_half_mirror row_mask:0xf bank_mask:0xf bound_ctrl:1
	s_nop 1
	v_add_f32_dpp v244, v244, v244 row_mirror row_mask:0xf bank_mask:0xf bound_ctrl:1
	v_mov_b32_e32 v245, v244
	s_nop 1
	v_permlane16_swap_b32_e32 v244, v245
	s_and_saveexec_b64 s[78:79], s[4:5]
	s_cbranch_execz .LBB0_628
	v_lshl_add_u64 v[246:247], s[72:73], 0, v[118:119]
	v_add_f32_e32 v244, v244, v245
	global_store_dword v[246:247], v244, off offset:-1024
.LBB0_628:
	s_or_b64 exec, exec, s[78:79]
	ds_read_b128 v[150:153], v132 offset:17408
	s_nop 0
	v_add_co_u32_e32 v154, vcc, s80, v122
	s_waitcnt vmcnt(7) lgkmcnt(0)
	v_pk_fma_f32 v[250:251], v[98:99], v[152:153], v[250:251]
	v_addc_co_u32_e32 v155, vcc, 0, v123, vcc
	v_pk_fma_f32 v[248:249], v[96:97], v[150:151], v[248:249]
	global_store_dwordx4 v[154:155], v[248:251], off
	v_mul_f32_e32 v150, v142, v248
	v_mul_f32_e32 v151, v143, v249
	v_pk_mul_f32 v[248:249], v[248:249], v[248:249]
	v_mul_f32_e32 v152, v144, v250
	v_mul_f32_e32 v153, v145, v251
	v_pk_mul_f32 v[250:251], v[250:251], v[250:251]
	v_add_f32_e32 v248, v248, v249
	v_add_f32_e32 v248, v250, v248
	v_add_f32_e32 v248, v251, v248
	v_add_co_u32_e32 v158, vcc, s81, v120
	s_nop 0
	v_add_f32_dpp v248, v248, v248 quad_perm:[1,0,3,2] row_mask:0xf bank_mask:0xf bound_ctrl:1
	v_addc_co_u32_e32 v159, vcc, 0, v121, vcc
	s_nop 0
	v_add_f32_dpp v248, v248, v248 quad_perm:[2,3,0,1] row_mask:0xf bank_mask:0xf bound_ctrl:1
	v_cvt_pk_bf16_f32 v150, v150, v151
	v_cvt_pk_bf16_f32 v151, v152, v153
	global_store_dwordx2 v[158:159], v[150:151], off
	s_nop 0
	v_add_f32_dpp v248, v248, v248 row_half_mirror row_mask:0xf bank_mask:0xf bound_ctrl:1
	s_nop 1
	v_add_f32_dpp v248, v248, v248 row_mirror row_mask:0xf bank_mask:0xf bound_ctrl:1
	v_mov_b32_e32 v249, v248
	s_nop 1
	v_permlane16_swap_b32_e32 v248, v249
	s_and_saveexec_b64 s[78:79], s[4:5]
	s_cbranch_execz .LBB0_630
	v_lshl_add_u64 v[250:251], s[72:73], 0, v[118:119]
	v_add_f32_e32 v248, v248, v249
	global_store_dword v[250:251], v248, off
.LBB0_630:
	s_or_b64 exec, exec, s[78:79]
	ds_read_b128 v[150:153], v132 offset:26112
	s_nop 0
	v_add_co_u32_e32 v124, vcc, s82, v122
	s_nop 1
	v_addc_co_u32_e32 v125, vcc, 0, v123, vcc
	v_add_co_u32_e32 v154, vcc, s83, v120
	s_waitcnt vmcnt(9) lgkmcnt(0)
	v_pk_fma_f32 v[122:123], v[98:99], v[152:153], v[254:255]
	v_addc_co_u32_e32 v155, vcc, 0, v121, vcc
	v_pk_fma_f32 v[120:121], v[96:97], v[150:151], v[252:253]
	global_store_dwordx4 v[124:125], v[120:123], off
	v_mul_f32_e32 v124, v142, v120
	v_mul_f32_e32 v125, v143, v121
	v_pk_mul_f32 v[120:121], v[120:121], v[120:121]
	v_mul_f32_e32 v252, v144, v122
	v_mul_f32_e32 v253, v145, v123
	v_pk_mul_f32 v[122:123], v[122:123], v[122:123]
	v_add_f32_e32 v120, v120, v121
	v_add_f32_e32 v120, v122, v120
	v_add_f32_e32 v120, v123, v120
	v_cvt_pk_bf16_f32 v124, v124, v125
	v_cvt_pk_bf16_f32 v125, v252, v253
	global_store_dwordx2 v[154:155], v[124:125], off
	s_nop 0
	v_add_f32_dpp v120, v120, v120 quad_perm:[1,0,3,2] row_mask:0xf bank_mask:0xf bound_ctrl:1
	s_nop 1
	v_add_f32_dpp v120, v120, v120 quad_perm:[2,3,0,1] row_mask:0xf bank_mask:0xf bound_ctrl:1
	s_nop 1
	v_add_f32_dpp v120, v120, v120 row_half_mirror row_mask:0xf bank_mask:0xf bound_ctrl:1
	s_nop 1
	v_add_f32_dpp v120, v120, v120 row_mirror row_mask:0xf bank_mask:0xf bound_ctrl:1
	v_mov_b32_e32 v121, v120
	s_nop 1
	v_permlane16_swap_b32_e32 v120, v121
	s_and_saveexec_b64 s[78:79], s[4:5]
	s_cbranch_execz .LBB0_623
	v_lshl_add_u64 v[122:123], s[72:73], 0, v[118:119]
	v_add_f32_e32 v120, v120, v121
	global_store_dword v[122:123], v120, off offset:1024
	s_branch .LBB0_623

.LBB0_634:
	v_lshl_add_u64 v[16:17], v[6:7], 0, s[58:59]
	global_load_dwordx4 v[24:27], v[16:17], off offset:512 nt
	v_add_co_u32_e32 v244, vcc, 0x20000, v16
	s_nop 1
	v_addc_co_u32_e32 v245, vcc, 0, v17, vcc
	global_load_dwordx4 v[244:247], v[244:245], off offset:512 nt
	v_add_co_u32_e32 v248, vcc, 0x40000, v16
	s_nop 1
	v_addc_co_u32_e32 v249, vcc, 0, v17, vcc
	global_load_dwordx4 v[248:251], v[248:249], off offset:512 nt
	v_add_co_u32_e32 v252, vcc, 0x60000, v16
	s_nop 1
	v_addc_co_u32_e32 v253, vcc, 0, v17, vcc
	global_load_dwordx4 v[252:255], v[252:253], off offset:512 nt
	ds_read_b128 v[28:31], v18
	v_lshl_add_u64 v[14:15], v[8:9], 0, s[58:59]
	v_lshl_add_u64 v[12:13], s[72:73], 0, v[4:5]
	v_add_co_u32_e32 v32, vcc, s15, v12
	s_waitcnt vmcnt(3) lgkmcnt(0)
	v_pk_fma_f32 v[26:27], v[2:3], v[30:31], v[26:27]
	v_pk_fma_f32 v[24:25], v[0:1], v[28:29], v[24:25]
	global_store_dwordx4 v[14:15], v[24:27], off offset:512
	v_mul_f32_e32 v23, v19, v24
	v_mul_f32_e32 v28, v20, v25
	v_pk_mul_f32 v[24:25], v[24:25], v[24:25]
	v_mul_f32_e32 v29, v21, v26
	v_mul_f32_e32 v30, v22, v27
	v_pk_mul_f32 v[26:27], v[26:27], v[26:27]
	v_cvt_pk_bf16_f32 v28, v23, v28
	v_add_f32_e32 v23, v24, v25
	v_add_f32_e32 v23, v26, v23
	v_add_f32_e32 v23, v27, v23
	v_addc_co_u32_e32 v33, vcc, 0, v13, vcc
	s_nop 0
	v_add_f32_dpp v23, v23, v23 quad_perm:[1,0,3,2] row_mask:0xf bank_mask:0xf bound_ctrl:1
	v_cvt_pk_bf16_f32 v29, v29, v30
	global_store_dwordx2 v[32:33], v[28:29], off offset:256
	s_nop 0
	v_add_f32_dpp v23, v23, v23 quad_perm:[2,3,0,1] row_mask:0xf bank_mask:0xf bound_ctrl:1
	s_nop 1
	v_add_f32_dpp v23, v23, v23 row_half_mirror row_mask:0xf bank_mask:0xf bound_ctrl:1
	s_nop 1
	v_add_f32_dpp v23, v23, v23 row_mirror row_mask:0xf bank_mask:0xf bound_ctrl:1
	v_mov_b32_e32 v24, v23
	s_nop 1
	v_permlane16_swap_b32_e32 v23, v24
	s_and_saveexec_b64 s[60:61], s[4:5]
	s_cbranch_execz .LBB0_636
	v_lshl_add_u64 v[26:27], s[72:73], 0, v[10:11]
	v_add_f32_e32 v23, v23, v24
	global_store_dword v[26:27], v23, off offset:-2048
.LBB0_636:
	s_or_b64 exec, exec, s[60:61]
	ds_read_b128 v[28:31], v18 offset:8704
	s_nop 0
	v_add_co_u32_e32 v32, vcc, s22, v14
	s_waitcnt vmcnt(5) lgkmcnt(0)
	v_pk_fma_f32 v[246:247], v[2:3], v[30:31], v[246:247]
	v_addc_co_u32_e32 v33, vcc, 0, v15, vcc
	v_pk_fma_f32 v[244:245], v[0:1], v[28:29], v[244:245]
	global_store_dwordx4 v[32:33], v[244:247], off offset:512
	v_mul_f32_e32 v23, v19, v244
	v_mul_f32_e32 v28, v20, v245
	v_pk_mul_f32 v[244:245], v[244:245], v[244:245]
	v_mul_f32_e32 v29, v21, v246
	v_mul_f32_e32 v30, v22, v247
	v_pk_mul_f32 v[246:247], v[246:247], v[246:247]
	v_cvt_pk_bf16_f32 v28, v23, v28
	v_add_f32_e32 v23, v244, v245
	v_add_f32_e32 v23, v246, v23
	v_add_f32_e32 v23, v247, v23
	v_add_co_u32_e32 v34, vcc, s33, v12
	s_nop 0
	v_add_f32_dpp v23, v23, v23 quad_perm:[1,0,3,2] row_mask:0xf bank_mask:0xf bound_ctrl:1
	v_addc_co_u32_e32 v35, vcc, 0, v13, vcc
	s_nop 0
	v_add_f32_dpp v23, v23, v23 quad_perm:[2,3,0,1] row_mask:0xf bank_mask:0xf bound_ctrl:1
	v_cvt_pk_bf16_f32 v29, v29, v30
	global_store_dwordx2 v[34:35], v[28:29], off offset:256
	s_nop 0
	v_add_f32_dpp v23, v23, v23 row_half_mirror row_mask:0xf bank_mask:0xf bound_ctrl:1
	s_nop 1
	v_add_f32_dpp v23, v23, v23 row_mirror row_mask:0xf bank_mask:0xf bound_ctrl:1
	v_mov_b32_e32 v244, v23
	s_nop 1
	v_permlane16_swap_b32_e32 v23, v244
	s_and_saveexec_b64 s[60:61], s[4:5]
	s_cbranch_execz .LBB0_638
	v_lshl_add_u64 v[246:247], s[72:73], 0, v[10:11]
	v_add_f32_e32 v23, v23, v244
	global_store_dword v[246:247], v23, off offset:-1024
.LBB0_638:
	s_or_b64 exec, exec, s[60:61]
	ds_read_b128 v[28:31], v18 offset:17408
	s_nop 0
	v_add_co_u32_e32 v32, vcc, s80, v14
	s_waitcnt vmcnt(7) lgkmcnt(0)
	v_pk_fma_f32 v[250:251], v[2:3], v[30:31], v[250:251]
	v_addc_co_u32_e32 v33, vcc, 0, v15, vcc
	v_pk_fma_f32 v[248:249], v[0:1], v[28:29], v[248:249]
	global_store_dwordx4 v[32:33], v[248:251], off offset:512
	v_mul_f32_e32 v23, v19, v248
	v_mul_f32_e32 v28, v20, v249
	v_pk_mul_f32 v[248:249], v[248:249], v[248:249]
	v_mul_f32_e32 v29, v21, v250
	v_mul_f32_e32 v30, v22, v251
	v_pk_mul_f32 v[250:251], v[250:251], v[250:251]
	v_cvt_pk_bf16_f32 v28, v23, v28
	v_add_f32_e32 v23, v248, v249
	v_add_f32_e32 v23, v250, v23
	v_add_f32_e32 v23, v251, v23
	v_add_co_u32_e32 v34, vcc, s81, v12
	s_nop 0
	v_add_f32_dpp v23, v23, v23 quad_perm:[1,0,3,2] row_mask:0xf bank_mask:0xf bound_ctrl:1
	v_addc_co_u32_e32 v35, vcc, 0, v13, vcc
	s_nop 0
	v_add_f32_dpp v23, v23, v23 quad_perm:[2,3,0,1] row_mask:0xf bank_mask:0xf bound_ctrl:1
	v_cvt_pk_bf16_f32 v29, v29, v30
	global_store_dwordx2 v[34:35], v[28:29], off offset:256
	s_nop 0
	v_add_f32_dpp v23, v23, v23 row_half_mirror row_mask:0xf bank_mask:0xf bound_ctrl:1
	s_nop 1
	v_add_f32_dpp v23, v23, v23 row_mirror row_mask:0xf bank_mask:0xf bound_ctrl:1
	v_mov_b32_e32 v248, v23
	s_nop 1
	v_permlane16_swap_b32_e32 v23, v248
	s_and_saveexec_b64 s[60:61], s[4:5]
	s_cbranch_execz .LBB0_640
	v_lshl_add_u64 v[250:251], s[72:73], 0, v[10:11]
	v_add_f32_e32 v23, v23, v248
	global_store_dword v[250:251], v23, off
.LBB0_640:
	s_or_b64 exec, exec, s[60:61]
	ds_read_b128 v[28:31], v18 offset:26112
	s_nop 0
	v_add_co_u32_e32 v16, vcc, s82, v14
	s_nop 1
	v_addc_co_u32_e32 v17, vcc, 0, v15, vcc
	v_add_co_u32_e32 v32, vcc, s83, v12
	s_waitcnt vmcnt(9) lgkmcnt(0)
	v_pk_fma_f32 v[14:15], v[2:3], v[30:31], v[254:255]
	v_addc_co_u32_e32 v33, vcc, 0, v13, vcc
	v_pk_fma_f32 v[12:13], v[0:1], v[28:29], v[252:253]
	global_store_dwordx4 v[16:17], v[12:15], off offset:512
	v_mul_f32_e32 v16, v19, v12
	v_mul_f32_e32 v17, v20, v13
	v_pk_mul_f32 v[12:13], v[12:13], v[12:13]
	v_mul_f32_e32 v23, v21, v14
	v_mul_f32_e32 v252, v22, v15
	v_pk_mul_f32 v[14:15], v[14:15], v[14:15]
	v_add_f32_e32 v12, v12, v13
	v_add_f32_e32 v12, v14, v12
	v_add_f32_e32 v12, v15, v12
	v_cvt_pk_bf16_f32 v16, v16, v17
	v_cvt_pk_bf16_f32 v17, v23, v252
	global_store_dwordx2 v[32:33], v[16:17], off offset:256
	s_nop 0
	v_add_f32_dpp v12, v12, v12 quad_perm:[1,0,3,2] row_mask:0xf bank_mask:0xf bound_ctrl:1
	s_nop 1
	v_add_f32_dpp v12, v12, v12 quad_perm:[2,3,0,1] row_mask:0xf bank_mask:0xf bound_ctrl:1
	s_nop 1
	v_add_f32_dpp v12, v12, v12 row_half_mirror row_mask:0xf bank_mask:0xf bound_ctrl:1
	s_nop 1
	v_add_f32_dpp v12, v12, v12 row_mirror row_mask:0xf bank_mask:0xf bound_ctrl:1
	v_mov_b32_e32 v13, v12
	s_nop 1
	v_permlane16_swap_b32_e32 v12, v13
	s_and_saveexec_b64 s[60:61], s[4:5]
	s_cbranch_execz .LBB0_633
	v_lshl_add_u64 v[14:15], s[72:73], 0, v[10:11]
	v_add_f32_e32 v12, v12, v13
	global_store_dword v[14:15], v12, off offset:1024
	s_branch .LBB0_633
